# 7.11 loop-edge rotation in the MLA loop: next tile's address math + 5 global loads issued in front of the loop-back barrier instead of behind it at the loop head
# speedup vs baseline: 1.0065x; 1.0065x over previous
.LBB0_556:
	v_add_f32_e32 v90, 0, v90
	v_add_f32_e32 v90, v91, v90
	v_add_f32_e32 v90, v92, v90
	v_add_f32_e32 v90, v93, v90
	v_add_f32_e32 v82, v82, v90
	v_add_f32_e32 v82, v83, v82
	v_add_f32_e32 v82, v84, v82
	v_add_f32_e32 v82, v85, v82
	v_add_f32_e32 v82, v86, v82
	v_add_f32_e32 v82, v87, v82
	v_add_f32_e32 v82, v88, v82
	v_add_f32_e32 v82, v89, v82
	v_add_f32_e32 v78, v78, v82
	v_add_f32_e32 v78, v79, v78
	v_add_f32_e32 v78, v80, v78
	v_add_f32_e32 v78, v81, v78
	v_add_f32_e32 v140, v140, v78
	v_add_f32_e32 v78, 0, v106
	v_add_f32_e32 v78, v107, v78
	v_add_f32_e32 v78, v108, v78
	v_add_f32_e32 v78, v109, v78
	v_add_f32_e32 v78, v98, v78
	v_add_f32_e32 v78, v99, v78
	v_add_f32_e32 v78, v100, v78
	v_add_f32_e32 v78, v101, v78
	v_add_f32_e32 v78, v102, v78
	v_add_f32_e32 v78, v103, v78
	v_add_f32_e32 v78, v104, v78
	v_add_f32_e32 v78, v105, v78
	v_add_f32_e32 v78, v94, v78
	v_add_f32_e32 v78, v95, v78
	v_add_f32_e32 v78, v96, v78
	v_add_f32_e32 v78, v97, v78
	s_addk_i32 s4, 0x80
	v_add_f32_e32 v141, v141, v78
	s_waitcnt lgkmcnt(0)
	s_cmpk_lg_i32 s4, 0x1080
	s_cselect_b64 s[2:3], -1, 0
	s_cmpk_lt_u32 s4, 0x1080
	s_cbranch_scc0 .Lmla_rot_nopf
	v_add_u32_e32 v10, s4, v137
	v_add_u32_e32 v18, s4, v117
	v_add_u32_e32 v34, s4, v115
	v_ashrrev_i32_e32 v11, 31, v10
	v_ashrrev_i32_e32 v19, 31, v18
	v_ashrrev_i32_e32 v35, 31, v34
	v_lshlrev_b64 v[14:15], 11, v[10:11]
	v_lshlrev_b64 v[22:23], 11, v[18:19]
	v_lshlrev_b64 v[34:35], 6, v[34:35]
	v_lshl_add_u64 v[10:11], v[118:119], 0, v[14:15]
	v_lshl_add_u64 v[14:15], v[120:121], 0, v[14:15]
	v_lshl_add_u64 v[18:19], v[118:119], 0, v[22:23]
	v_lshl_add_u64 v[22:23], v[120:121], 0, v[22:23]
	v_lshl_add_u64 v[34:35], v[122:123], 0, v[34:35]
	global_load_dwordx4 v[10:13], v[10:11], off
	global_load_dwordx4 v[14:17], v[14:15], off
	global_load_dwordx4 v[18:21], v[18:19], off
	global_load_dwordx4 v[22:25], v[22:23], off
	global_load_dwordx4 v[34:37], v[34:35], off
.Lmla_rot_nopf:
	s_cmpk_lg_i32 s4, 0x1100
	s_barrier
	s_cbranch_scc0 .LBB0_554
	s_branch .LBB0_559
